# accumulators cleared once per tile (zero-trip test first; dead-path nop keeps every K-loop at its baseline 8-byte phase) + EpiResid prefetch
# speedup vs baseline: 1.0167x; 1.0167x over previous
; template <class Epi, class Sched, bool ALIGN_EPI = false, bool SP2 = false>
; __device__ __forceinline__ void gemm_phase(PG8_LAS unsigned char* lds, const Gemm g, const Sched& S, const Epi& E, int tid_in) {
;     ...
; #pragma unroll
;         for (int a = 0; a < 2; ++a)
; #pragma unroll
;             for (int b = 0; b < 2; ++b)
; #pragma unroll
;                 for (int m = 0; m < 4; ++m)
; #pragma unroll
;                     for (int n = 0; n < 2; ++n) acc[a][b][m][n] = (f32x4){0.f, 0.f, 0.f, 0.f};
.LBB0_186:
	s_andn2_b64 vcc, exec, s[24:25]
	s_cbranch_vccz .Lkeep_acc_1
	v_mov_b32_e32 v127, 0
	v_mov_b32_e32 v126, v127
	v_mov_b32_e32 v125, v127
	v_mov_b32_e32 v124, v127
	v_mov_b32_e32 v123, v127
	v_mov_b32_e32 v122, v127
	v_mov_b32_e32 v121, v127
	v_mov_b32_e32 v120, v127
	v_mov_b32_e32 v111, v127
	v_mov_b32_e32 v110, v127
	v_mov_b32_e32 v109, v127
	v_mov_b32_e32 v108, v127
	v_mov_b32_e32 v107, v127
	v_mov_b32_e32 v106, v127
	v_mov_b32_e32 v105, v127
	v_mov_b32_e32 v104, v127
	v_mov_b32_e32 v95, v127
	v_mov_b32_e32 v94, v127
	v_mov_b32_e32 v93, v127
	v_mov_b32_e32 v92, v127
	v_mov_b32_e32 v91, v127
	v_mov_b32_e32 v90, v127
	v_mov_b32_e32 v89, v127
	v_mov_b32_e32 v88, v127
	v_mov_b32_e32 v79, v127
	v_mov_b32_e32 v78, v127
	v_mov_b32_e32 v77, v127
	v_mov_b32_e32 v76, v127
	v_mov_b32_e32 v75, v127
	v_mov_b32_e32 v74, v127
	v_mov_b32_e32 v73, v127
	v_mov_b32_e32 v72, v127
	v_mov_b32_e32 v119, v127
	v_mov_b32_e32 v118, v127
	v_mov_b32_e32 v117, v127
	v_mov_b32_e32 v116, v127
	v_mov_b32_e32 v115, v127
	v_mov_b32_e32 v114, v127
	v_mov_b32_e32 v113, v127
	v_mov_b32_e32 v112, v127
	v_mov_b32_e32 v103, v127
	v_mov_b32_e32 v102, v127
	v_mov_b32_e32 v101, v127
	v_mov_b32_e32 v100, v127
	v_mov_b32_e32 v99, v127
	v_mov_b32_e32 v98, v127
	v_mov_b32_e32 v97, v127
	v_mov_b32_e32 v96, v127
	v_mov_b32_e32 v87, v127
	v_mov_b32_e32 v86, v127
	v_mov_b32_e32 v85, v127
	v_mov_b32_e32 v84, v127
	v_mov_b32_e32 v83, v127
	v_mov_b32_e32 v82, v127
	v_mov_b32_e32 v81, v127
	v_mov_b32_e32 v80, v127
	v_mov_b32_e32 v71, v127
	v_mov_b32_e32 v70, v127
	v_mov_b32_e32 v69, v127
	v_mov_b32_e32 v68, v127
	v_mov_b32_e32 v67, v127
	v_mov_b32_e32 v66, v127
	v_mov_b32_e32 v65, v127
	v_mov_b32_e32 v64, v127
	v_mov_b32_e32 v63, v127
	v_mov_b32_e32 v62, v127
	v_mov_b32_e32 v61, v127
	v_mov_b32_e32 v60, v127
	v_mov_b32_e32 v59, v127
	v_mov_b32_e32 v58, v127
	v_mov_b32_e32 v57, v127
	v_mov_b32_e32 v56, v127
	v_mov_b32_e32 v47, v127
	v_mov_b32_e32 v46, v127
	v_mov_b32_e32 v45, v127
	v_mov_b32_e32 v44, v127
	v_mov_b32_e32 v43, v127
	v_mov_b32_e32 v42, v127
	v_mov_b32_e32 v41, v127
	v_mov_b32_e32 v40, v127
	v_mov_b32_e32 v31, v127
	v_mov_b32_e32 v30, v127
	v_mov_b32_e32 v29, v127
	v_mov_b32_e32 v28, v127
	v_mov_b32_e32 v27, v127
	v_mov_b32_e32 v26, v127
	v_mov_b32_e32 v25, v127
	v_mov_b32_e32 v24, v127
	v_mov_b32_e32 v15, v127
	v_mov_b32_e32 v14, v127
	v_mov_b32_e32 v13, v127
	v_mov_b32_e32 v12, v127
	v_mov_b32_e32 v11, v127
	v_mov_b32_e32 v10, v127
	v_mov_b32_e32 v9, v127
	v_mov_b32_e32 v8, v127
	v_mov_b32_e32 v55, v127
	v_mov_b32_e32 v54, v127
	v_mov_b32_e32 v53, v127
	v_mov_b32_e32 v52, v127
	v_mov_b32_e32 v51, v127
	v_mov_b32_e32 v50, v127
	v_mov_b32_e32 v49, v127
	v_mov_b32_e32 v48, v127
	v_mov_b32_e32 v39, v127
	v_mov_b32_e32 v38, v127
	v_mov_b32_e32 v37, v127
	v_mov_b32_e32 v36, v127
	v_mov_b32_e32 v35, v127
	v_mov_b32_e32 v34, v127
	v_mov_b32_e32 v33, v127
	v_mov_b32_e32 v32, v127
	v_mov_b32_e32 v23, v127
	v_mov_b32_e32 v22, v127
	v_mov_b32_e32 v21, v127
	v_mov_b32_e32 v20, v127
	v_mov_b32_e32 v19, v127
	v_mov_b32_e32 v18, v127
	v_mov_b32_e32 v17, v127
	v_mov_b32_e32 v16, v127
	v_mov_b32_e32 v7, v127
	v_mov_b32_e32 v6, v127
	v_mov_b32_e32 v5, v127
	v_mov_b32_e32 v4, v127
	v_mov_b32_e32 v3, v127
	v_mov_b32_e32 v2, v127
	v_mov_b32_e32 v1, v127
	v_mov_b32_e32 v0, v127
	s_branch .LBB0_189
	s_nop 0

; template <class Epi, class Sched, bool ALIGN_EPI = false, bool SP2 = false>
; __device__ __forceinline__ void gemm_phase(PG8_LAS unsigned char* lds, const Gemm g, const Sched& S, const Epi& E, int tid_in) {
;     ...
; #pragma unroll
;         for (int a = 0; a < 2; ++a)
; #pragma unroll
;             for (int b = 0; b < 2; ++b)
; #pragma unroll
;                 for (int m = 0; m < 4; ++m)
; #pragma unroll
;                     for (int n = 0; n < 2; ++n) acc[a][b][m][n] = (f32x4){0.f, 0.f, 0.f, 0.f};
.LBB0_363:
	s_andn2_b64 vcc, exec, s[40:41]
	s_cbranch_vccz .Lkeep_acc_2
	v_mov_b32_e32 v123, 0
	v_mov_b32_e32 v122, v123
	v_mov_b32_e32 v121, v123
	v_mov_b32_e32 v120, v123
	v_mov_b32_e32 v127, v123
	v_mov_b32_e32 v126, v123
	v_mov_b32_e32 v125, v123
	v_mov_b32_e32 v124, v123
	v_mov_b32_e32 v111, v123
	v_mov_b32_e32 v110, v123
	v_mov_b32_e32 v109, v123
	v_mov_b32_e32 v108, v123
	v_mov_b32_e32 v107, v123
	v_mov_b32_e32 v106, v123
	v_mov_b32_e32 v105, v123
	v_mov_b32_e32 v104, v123
	v_mov_b32_e32 v95, v123
	v_mov_b32_e32 v94, v123
	v_mov_b32_e32 v93, v123
	v_mov_b32_e32 v92, v123
	v_mov_b32_e32 v91, v123
	v_mov_b32_e32 v90, v123
	v_mov_b32_e32 v89, v123
	v_mov_b32_e32 v88, v123
	v_mov_b32_e32 v79, v123
	v_mov_b32_e32 v78, v123
	v_mov_b32_e32 v77, v123
	v_mov_b32_e32 v76, v123
	v_mov_b32_e32 v75, v123
	v_mov_b32_e32 v74, v123
	v_mov_b32_e32 v73, v123
	v_mov_b32_e32 v72, v123
	v_mov_b32_e32 v119, v123
	v_mov_b32_e32 v118, v123
	v_mov_b32_e32 v117, v123
	v_mov_b32_e32 v116, v123
	v_mov_b32_e32 v115, v123
	v_mov_b32_e32 v114, v123
	v_mov_b32_e32 v113, v123
	v_mov_b32_e32 v112, v123
	v_mov_b32_e32 v103, v123
	v_mov_b32_e32 v102, v123
	v_mov_b32_e32 v101, v123
	v_mov_b32_e32 v100, v123
	v_mov_b32_e32 v99, v123
	v_mov_b32_e32 v98, v123
	v_mov_b32_e32 v97, v123
	v_mov_b32_e32 v96, v123
	v_mov_b32_e32 v87, v123
	v_mov_b32_e32 v86, v123
	v_mov_b32_e32 v85, v123
	v_mov_b32_e32 v84, v123
	v_mov_b32_e32 v83, v123
	v_mov_b32_e32 v82, v123
	v_mov_b32_e32 v81, v123
	v_mov_b32_e32 v80, v123
	v_mov_b32_e32 v71, v123
	v_mov_b32_e32 v70, v123
	v_mov_b32_e32 v69, v123
	v_mov_b32_e32 v68, v123
	v_mov_b32_e32 v67, v123
	v_mov_b32_e32 v66, v123
	v_mov_b32_e32 v65, v123
	v_mov_b32_e32 v64, v123
	v_mov_b32_e32 v63, v123
	v_mov_b32_e32 v62, v123
	v_mov_b32_e32 v61, v123
	v_mov_b32_e32 v60, v123
	v_mov_b32_e32 v59, v123
	v_mov_b32_e32 v58, v123
	v_mov_b32_e32 v57, v123
	v_mov_b32_e32 v56, v123
	v_mov_b32_e32 v47, v123
	v_mov_b32_e32 v46, v123
	v_mov_b32_e32 v45, v123
	v_mov_b32_e32 v44, v123
	v_mov_b32_e32 v43, v123
	v_mov_b32_e32 v42, v123
	v_mov_b32_e32 v41, v123
	v_mov_b32_e32 v40, v123
	v_mov_b32_e32 v31, v123
	v_mov_b32_e32 v30, v123
	v_mov_b32_e32 v29, v123
	v_mov_b32_e32 v28, v123
	v_mov_b32_e32 v27, v123
	v_mov_b32_e32 v26, v123
	v_mov_b32_e32 v25, v123
	v_mov_b32_e32 v24, v123
	v_mov_b32_e32 v15, v123
	v_mov_b32_e32 v14, v123
	v_mov_b32_e32 v13, v123
	v_mov_b32_e32 v12, v123
	v_mov_b32_e32 v11, v123
	v_mov_b32_e32 v10, v123
	v_mov_b32_e32 v9, v123
	v_mov_b32_e32 v8, v123
	v_mov_b32_e32 v55, v123
	v_mov_b32_e32 v54, v123
	v_mov_b32_e32 v53, v123
	v_mov_b32_e32 v52, v123
	v_mov_b32_e32 v51, v123
	v_mov_b32_e32 v50, v123
	v_mov_b32_e32 v49, v123
	v_mov_b32_e32 v48, v123
	v_mov_b32_e32 v39, v123
	v_mov_b32_e32 v38, v123
	v_mov_b32_e32 v37, v123
	v_mov_b32_e32 v36, v123
	v_mov_b32_e32 v35, v123
	v_mov_b32_e32 v34, v123
	v_mov_b32_e32 v33, v123
	v_mov_b32_e32 v32, v123
	v_mov_b32_e32 v23, v123
	v_mov_b32_e32 v22, v123
	v_mov_b32_e32 v21, v123
	v_mov_b32_e32 v20, v123
	v_mov_b32_e32 v19, v123
	v_mov_b32_e32 v18, v123
	v_mov_b32_e32 v17, v123
	v_mov_b32_e32 v16, v123
	v_mov_b32_e32 v7, v123
	v_mov_b32_e32 v6, v123
	v_mov_b32_e32 v5, v123
	v_mov_b32_e32 v4, v123
	v_mov_b32_e32 v3, v123
	v_mov_b32_e32 v2, v123
	v_mov_b32_e32 v1, v123
	v_mov_b32_e32 v0, v123
	s_branch .LBB0_366
	s_nop 0

; template <class Epi, class Sched, bool ALIGN_EPI = false, bool SP2 = false>
; __device__ __forceinline__ void gemm_phase(PG8_LAS unsigned char* lds, const Gemm g, const Sched& S, const Epi& E, int tid_in) {
;     ...
; #pragma unroll
;         for (int a = 0; a < 2; ++a)
; #pragma unroll
;             for (int b = 0; b < 2; ++b)
; #pragma unroll
;                 for (int m = 0; m < 4; ++m)
; #pragma unroll
;                     for (int n = 0; n < 2; ++n) acc[a][b][m][n] = (f32x4){0.f, 0.f, 0.f, 0.f};
.LBB0_989:
	s_andn2_b64 vcc, exec, s[36:37]
	s_cbranch_vccz .Lkeep_acc_3
	v_mov_b32_e32 v135, 0
	v_mov_b32_e32 v134, v135
	v_mov_b32_e32 v133, v135
	v_mov_b32_e32 v132, v135
	v_mov_b32_e32 v131, v135
	v_mov_b32_e32 v130, v135
	v_mov_b32_e32 v129, v135
	v_mov_b32_e32 v128, v135
	v_mov_b32_e32 v127, v135
	v_mov_b32_e32 v126, v135
	v_mov_b32_e32 v125, v135
	v_mov_b32_e32 v124, v135
	v_mov_b32_e32 v123, v135
	v_mov_b32_e32 v122, v135
	v_mov_b32_e32 v121, v135
	v_mov_b32_e32 v120, v135
	v_mov_b32_e32 v119, v135
	v_mov_b32_e32 v118, v135
	v_mov_b32_e32 v117, v135
	v_mov_b32_e32 v116, v135
	v_mov_b32_e32 v115, v135
	v_mov_b32_e32 v114, v135
	v_mov_b32_e32 v113, v135
	v_mov_b32_e32 v112, v135
	v_mov_b32_e32 v111, v135
	v_mov_b32_e32 v110, v135
	v_mov_b32_e32 v109, v135
	v_mov_b32_e32 v108, v135
	v_mov_b32_e32 v103, v135
	v_mov_b32_e32 v102, v135
	v_mov_b32_e32 v101, v135
	v_mov_b32_e32 v100, v135
	v_mov_b32_e32 v63, v135
	v_mov_b32_e32 v62, v135
	v_mov_b32_e32 v61, v135
	v_mov_b32_e32 v60, v135
	v_mov_b32_e32 v59, v135
	v_mov_b32_e32 v58, v135
	v_mov_b32_e32 v57, v135
	v_mov_b32_e32 v56, v135
	v_mov_b32_e32 v55, v135
	v_mov_b32_e32 v54, v135
	v_mov_b32_e32 v53, v135
	v_mov_b32_e32 v52, v135
	v_mov_b32_e32 v51, v135
	v_mov_b32_e32 v50, v135
	v_mov_b32_e32 v49, v135
	v_mov_b32_e32 v48, v135
	v_mov_b32_e32 v47, v135
	v_mov_b32_e32 v46, v135
	v_mov_b32_e32 v45, v135
	v_mov_b32_e32 v44, v135
	v_mov_b32_e32 v43, v135
	v_mov_b32_e32 v42, v135
	v_mov_b32_e32 v41, v135
	v_mov_b32_e32 v40, v135
	v_mov_b32_e32 v39, v135
	v_mov_b32_e32 v38, v135
	v_mov_b32_e32 v37, v135
	v_mov_b32_e32 v36, v135
	v_mov_b32_e32 v35, v135
	v_mov_b32_e32 v34, v135
	v_mov_b32_e32 v33, v135
	v_mov_b32_e32 v32, v135
	v_mov_b32_e32 v95, v135
	v_mov_b32_e32 v94, v135
	v_mov_b32_e32 v93, v135
	v_mov_b32_e32 v92, v135
	v_mov_b32_e32 v91, v135
	v_mov_b32_e32 v90, v135
	v_mov_b32_e32 v89, v135
	v_mov_b32_e32 v88, v135
	v_mov_b32_e32 v87, v135
	v_mov_b32_e32 v86, v135
	v_mov_b32_e32 v85, v135
	v_mov_b32_e32 v84, v135
	v_mov_b32_e32 v83, v135
	v_mov_b32_e32 v82, v135
	v_mov_b32_e32 v81, v135
	v_mov_b32_e32 v80, v135
	v_mov_b32_e32 v79, v135
	v_mov_b32_e32 v78, v135
	v_mov_b32_e32 v77, v135
	v_mov_b32_e32 v76, v135
	v_mov_b32_e32 v75, v135
	v_mov_b32_e32 v74, v135
	v_mov_b32_e32 v73, v135
	v_mov_b32_e32 v72, v135
	v_mov_b32_e32 v71, v135
	v_mov_b32_e32 v70, v135
	v_mov_b32_e32 v69, v135
	v_mov_b32_e32 v68, v135
	v_mov_b32_e32 v67, v135
	v_mov_b32_e32 v66, v135
	v_mov_b32_e32 v65, v135
	v_mov_b32_e32 v64, v135
	v_mov_b32_e32 v31, v135
	v_mov_b32_e32 v30, v135
	v_mov_b32_e32 v29, v135
	v_mov_b32_e32 v28, v135
	v_mov_b32_e32 v27, v135
	v_mov_b32_e32 v26, v135
	v_mov_b32_e32 v25, v135
	v_mov_b32_e32 v24, v135
	v_mov_b32_e32 v23, v135
	v_mov_b32_e32 v22, v135
	v_mov_b32_e32 v21, v135
	v_mov_b32_e32 v20, v135
	v_mov_b32_e32 v19, v135
	v_mov_b32_e32 v18, v135
	v_mov_b32_e32 v17, v135
	v_mov_b32_e32 v16, v135
	v_mov_b32_e32 v15, v135
	v_mov_b32_e32 v14, v135
	v_mov_b32_e32 v13, v135
	v_mov_b32_e32 v12, v135
	v_mov_b32_e32 v11, v135
	v_mov_b32_e32 v10, v135
	v_mov_b32_e32 v9, v135
	v_mov_b32_e32 v8, v135
	v_mov_b32_e32 v7, v135
	v_mov_b32_e32 v6, v135
	v_mov_b32_e32 v5, v135
	v_mov_b32_e32 v4, v135
	v_mov_b32_e32 v3, v135
	v_mov_b32_e32 v2, v135
	v_mov_b32_e32 v1, v135
	v_mov_b32_e32 v0, v135
	s_branch .LBB0_993
	s_nop 0

; template <class Epi, class Sched, bool ALIGN_EPI = false, bool SP2 = false>
; __device__ __forceinline__ void gemm_phase(PG8_LAS unsigned char* lds, const Gemm g, const Sched& S, const Epi& E, int tid_in) {
;     ...
; #pragma unroll
;         for (int a = 0; a < 2; ++a)
; #pragma unroll
;             for (int b = 0; b < 2; ++b)
; #pragma unroll
;                 for (int m = 0; m < 4; ++m)
; #pragma unroll
;                     for (int n = 0; n < 2; ++n) acc[a][b][m][n] = (f32x4){0.f, 0.f, 0.f, 0.f};
.LBB0_1242:
	s_andn2_b64 vcc, exec, s[16:17]
	s_cbranch_vccz .Lkeep_acc_4
	v_mov_b32_e32 v123, 0
	v_mov_b32_e32 v122, v123
	v_mov_b32_e32 v121, v123
	v_mov_b32_e32 v120, v123
	v_mov_b32_e32 v127, v123
	v_mov_b32_e32 v126, v123
	v_mov_b32_e32 v125, v123
	v_mov_b32_e32 v124, v123
	v_mov_b32_e32 v111, v123
	v_mov_b32_e32 v110, v123
	v_mov_b32_e32 v109, v123
	v_mov_b32_e32 v108, v123
	v_mov_b32_e32 v107, v123
	v_mov_b32_e32 v106, v123
	v_mov_b32_e32 v105, v123
	v_mov_b32_e32 v104, v123
	v_mov_b32_e32 v95, v123
	v_mov_b32_e32 v94, v123
	v_mov_b32_e32 v93, v123
	v_mov_b32_e32 v92, v123
	v_mov_b32_e32 v91, v123
	v_mov_b32_e32 v90, v123
	v_mov_b32_e32 v89, v123
	v_mov_b32_e32 v88, v123
	v_mov_b32_e32 v79, v123
	v_mov_b32_e32 v78, v123
	v_mov_b32_e32 v77, v123
	v_mov_b32_e32 v76, v123
	v_mov_b32_e32 v75, v123
	v_mov_b32_e32 v74, v123
	v_mov_b32_e32 v73, v123
	v_mov_b32_e32 v72, v123
	v_mov_b32_e32 v119, v123
	v_mov_b32_e32 v118, v123
	v_mov_b32_e32 v117, v123
	v_mov_b32_e32 v116, v123
	v_mov_b32_e32 v115, v123
	v_mov_b32_e32 v114, v123
	v_mov_b32_e32 v113, v123
	v_mov_b32_e32 v112, v123
	v_mov_b32_e32 v103, v123
	v_mov_b32_e32 v102, v123
	v_mov_b32_e32 v101, v123
	v_mov_b32_e32 v100, v123
	v_mov_b32_e32 v99, v123
	v_mov_b32_e32 v98, v123
	v_mov_b32_e32 v97, v123
	v_mov_b32_e32 v96, v123
	v_mov_b32_e32 v87, v123
	v_mov_b32_e32 v86, v123
	v_mov_b32_e32 v85, v123
	v_mov_b32_e32 v84, v123
	v_mov_b32_e32 v83, v123
	v_mov_b32_e32 v82, v123
	v_mov_b32_e32 v81, v123
	v_mov_b32_e32 v80, v123
	v_mov_b32_e32 v71, v123
	v_mov_b32_e32 v70, v123
	v_mov_b32_e32 v69, v123
	v_mov_b32_e32 v68, v123
	v_mov_b32_e32 v67, v123
	v_mov_b32_e32 v66, v123
	v_mov_b32_e32 v65, v123
	v_mov_b32_e32 v64, v123
	v_mov_b32_e32 v63, v123
	v_mov_b32_e32 v62, v123
	v_mov_b32_e32 v61, v123
	v_mov_b32_e32 v60, v123
	v_mov_b32_e32 v59, v123
	v_mov_b32_e32 v58, v123
	v_mov_b32_e32 v57, v123
	v_mov_b32_e32 v56, v123
	v_mov_b32_e32 v47, v123
	v_mov_b32_e32 v46, v123
	v_mov_b32_e32 v45, v123
	v_mov_b32_e32 v44, v123
	v_mov_b32_e32 v43, v123
	v_mov_b32_e32 v42, v123
	v_mov_b32_e32 v41, v123
	v_mov_b32_e32 v40, v123
	v_mov_b32_e32 v31, v123
	v_mov_b32_e32 v30, v123
	v_mov_b32_e32 v29, v123
	v_mov_b32_e32 v28, v123
	v_mov_b32_e32 v27, v123
	v_mov_b32_e32 v26, v123
	v_mov_b32_e32 v25, v123
	v_mov_b32_e32 v24, v123
	v_mov_b32_e32 v15, v123
	v_mov_b32_e32 v14, v123
	v_mov_b32_e32 v13, v123
	v_mov_b32_e32 v12, v123
	v_mov_b32_e32 v11, v123
	v_mov_b32_e32 v10, v123
	v_mov_b32_e32 v9, v123
	v_mov_b32_e32 v8, v123
	v_mov_b32_e32 v55, v123
	v_mov_b32_e32 v54, v123
	v_mov_b32_e32 v53, v123
	v_mov_b32_e32 v52, v123
	v_mov_b32_e32 v51, v123
	v_mov_b32_e32 v50, v123
	v_mov_b32_e32 v49, v123
	v_mov_b32_e32 v48, v123
	v_mov_b32_e32 v39, v123
	v_mov_b32_e32 v38, v123
	v_mov_b32_e32 v37, v123
	v_mov_b32_e32 v36, v123
	v_mov_b32_e32 v35, v123
	v_mov_b32_e32 v34, v123
	v_mov_b32_e32 v33, v123
	v_mov_b32_e32 v32, v123
	v_mov_b32_e32 v23, v123
	v_mov_b32_e32 v22, v123
	v_mov_b32_e32 v21, v123
	v_mov_b32_e32 v20, v123
	v_mov_b32_e32 v19, v123
	v_mov_b32_e32 v18, v123
	v_mov_b32_e32 v17, v123
	v_mov_b32_e32 v16, v123
	v_mov_b32_e32 v7, v123
	v_mov_b32_e32 v6, v123
	v_mov_b32_e32 v5, v123
	v_mov_b32_e32 v4, v123
	v_mov_b32_e32 v3, v123
	v_mov_b32_e32 v2, v123
	v_mov_b32_e32 v1, v123
	v_mov_b32_e32 v0, v123
	s_branch .LBB0_1245
	s_nop 0

; template <class Epi, class Sched, bool ALIGN_EPI = false, bool SP2 = false>
; __device__ __forceinline__ void gemm_phase(PG8_LAS unsigned char* lds, const Gemm g, const Sched& S, const Epi& E, int tid_in) {
;     ...
; #pragma unroll
;         for (int a = 0; a < 2; ++a)
; #pragma unroll
;             for (int b = 0; b < 2; ++b)
; #pragma unroll
;                 for (int m = 0; m < 4; ++m)
; #pragma unroll
;                     for (int n = 0; n < 2; ++n) acc[a][b][m][n] = (f32x4){0.f, 0.f, 0.f, 0.f};
.LBB0_1580:
	s_andn2_b64 vcc, exec, s[22:23]
	s_cbranch_vccz .Lkeep_acc_5
	v_mov_b32_e32 v123, 0
	v_mov_b32_e32 v122, v123
	v_mov_b32_e32 v121, v123
	v_mov_b32_e32 v120, v123
	v_mov_b32_e32 v127, v123
	v_mov_b32_e32 v126, v123
	v_mov_b32_e32 v125, v123
	v_mov_b32_e32 v124, v123
	v_mov_b32_e32 v111, v123
	v_mov_b32_e32 v110, v123
	v_mov_b32_e32 v109, v123
	v_mov_b32_e32 v108, v123
	v_mov_b32_e32 v107, v123
	v_mov_b32_e32 v106, v123
	v_mov_b32_e32 v105, v123
	v_mov_b32_e32 v104, v123
	v_mov_b32_e32 v95, v123
	v_mov_b32_e32 v94, v123
	v_mov_b32_e32 v93, v123
	v_mov_b32_e32 v92, v123
	v_mov_b32_e32 v91, v123
	v_mov_b32_e32 v90, v123
	v_mov_b32_e32 v89, v123
	v_mov_b32_e32 v88, v123
	v_mov_b32_e32 v79, v123
	v_mov_b32_e32 v78, v123
	v_mov_b32_e32 v77, v123
	v_mov_b32_e32 v76, v123
	v_mov_b32_e32 v75, v123
	v_mov_b32_e32 v74, v123
	v_mov_b32_e32 v73, v123
	v_mov_b32_e32 v72, v123
	v_mov_b32_e32 v119, v123
	v_mov_b32_e32 v118, v123
	v_mov_b32_e32 v117, v123
	v_mov_b32_e32 v116, v123
	v_mov_b32_e32 v115, v123
	v_mov_b32_e32 v114, v123
	v_mov_b32_e32 v113, v123
	v_mov_b32_e32 v112, v123
	v_mov_b32_e32 v103, v123
	v_mov_b32_e32 v102, v123
	v_mov_b32_e32 v101, v123
	v_mov_b32_e32 v100, v123
	v_mov_b32_e32 v99, v123
	v_mov_b32_e32 v98, v123
	v_mov_b32_e32 v97, v123
	v_mov_b32_e32 v96, v123
	v_mov_b32_e32 v87, v123
	v_mov_b32_e32 v86, v123
	v_mov_b32_e32 v85, v123
	v_mov_b32_e32 v84, v123
	v_mov_b32_e32 v83, v123
	v_mov_b32_e32 v82, v123
	v_mov_b32_e32 v81, v123
	v_mov_b32_e32 v80, v123
	v_mov_b32_e32 v71, v123
	v_mov_b32_e32 v70, v123
	v_mov_b32_e32 v69, v123
	v_mov_b32_e32 v68, v123
	v_mov_b32_e32 v67, v123
	v_mov_b32_e32 v66, v123
	v_mov_b32_e32 v65, v123
	v_mov_b32_e32 v64, v123
	v_mov_b32_e32 v63, v123
	v_mov_b32_e32 v62, v123
	v_mov_b32_e32 v61, v123
	v_mov_b32_e32 v60, v123
	v_mov_b32_e32 v59, v123
	v_mov_b32_e32 v58, v123
	v_mov_b32_e32 v57, v123
	v_mov_b32_e32 v56, v123
	v_mov_b32_e32 v47, v123
	v_mov_b32_e32 v46, v123
	v_mov_b32_e32 v45, v123
	v_mov_b32_e32 v44, v123
	v_mov_b32_e32 v43, v123
	v_mov_b32_e32 v42, v123
	v_mov_b32_e32 v41, v123
	v_mov_b32_e32 v40, v123
	v_mov_b32_e32 v31, v123
	v_mov_b32_e32 v30, v123
	v_mov_b32_e32 v29, v123
	v_mov_b32_e32 v28, v123
	v_mov_b32_e32 v27, v123
	v_mov_b32_e32 v26, v123
	v_mov_b32_e32 v25, v123
	v_mov_b32_e32 v24, v123
	v_mov_b32_e32 v15, v123
	v_mov_b32_e32 v14, v123
	v_mov_b32_e32 v13, v123
	v_mov_b32_e32 v12, v123
	v_mov_b32_e32 v11, v123
	v_mov_b32_e32 v10, v123
	v_mov_b32_e32 v9, v123
	v_mov_b32_e32 v8, v123
	v_mov_b32_e32 v55, v123
	v_mov_b32_e32 v54, v123
	v_mov_b32_e32 v53, v123
	v_mov_b32_e32 v52, v123
	v_mov_b32_e32 v51, v123
	v_mov_b32_e32 v50, v123
	v_mov_b32_e32 v49, v123
	v_mov_b32_e32 v48, v123
	v_mov_b32_e32 v39, v123
	v_mov_b32_e32 v38, v123
	v_mov_b32_e32 v37, v123
	v_mov_b32_e32 v36, v123
	v_mov_b32_e32 v35, v123
	v_mov_b32_e32 v34, v123
	v_mov_b32_e32 v33, v123
	v_mov_b32_e32 v32, v123
	v_mov_b32_e32 v23, v123
	v_mov_b32_e32 v22, v123
	v_mov_b32_e32 v21, v123
	v_mov_b32_e32 v20, v123
	v_mov_b32_e32 v19, v123
	v_mov_b32_e32 v18, v123
	v_mov_b32_e32 v17, v123
	v_mov_b32_e32 v16, v123
	v_mov_b32_e32 v7, v123
	v_mov_b32_e32 v6, v123
	v_mov_b32_e32 v5, v123
	v_mov_b32_e32 v4, v123
	v_mov_b32_e32 v3, v123
	v_mov_b32_e32 v2, v123
	v_mov_b32_e32 v1, v123
	v_mov_b32_e32 v0, v123
	s_branch .LBB0_1583
	s_nop 0
